# v58 + MLA softmax section: v_exp and plain VALU (row-sum adds, bf16 packs) strictly alternated instead of runs of 8 exps then 7 plain ops
# baseline (speedup 1.0000x reference)
.LBB0_1482:
	v_exp_f32_e32 v66, v66
	v_exp_f32_e32 v67, v67
	v_exp_f32_e32 v68, v68
	v_exp_f32_e32 v69, v69
	v_exp_f32_e32 v70, v70
	v_exp_f32_e32 v71, v71
	v_exp_f32_e32 v72, v72
	v_exp_f32_e32 v73, v73
	v_exp_f32_e32 v74, v74
	v_pk_add_f32 v[154:155], v[66:67], v[68:69]
	v_exp_f32_e32 v75, v75
	v_pk_add_f32 v[156:157], v[70:71], v[72:73]
	v_exp_f32_e32 v76, v76
	v_pk_add_f32 v[158:159], v[154:155], v[156:157]
	v_exp_f32_e32 v77, v77
	v_cvt_pk_bf16_f32 v66, v66, v67
	v_exp_f32_e32 v78, v78
	v_cvt_pk_bf16_f32 v67, v68, v69
	v_exp_f32_e32 v79, v79
	v_cvt_pk_bf16_f32 v68, v70, v71
	v_exp_f32_e32 v80, v80
	v_cvt_pk_bf16_f32 v69, v72, v73
	v_exp_f32_e32 v81, v81
	v_exp_f32_e32 v82, v82
	v_mfma_f32_32x32x16_bf16 v[18:33], v[66:69], v[150:153], v[18:33]
	v_exp_f32_e32 v83, v83
	v_pk_add_f32 v[154:155], v[74:75], v[76:77]
	v_exp_f32_e32 v84, v84
	v_pk_add_f32 v[156:157], v[78:79], v[80:81]
	v_exp_f32_e32 v85, v85
	v_pk_add_f32 v[160:161], v[154:155], v[156:157]
	s_waitcnt lgkmcnt(6)
	v_mfma_f32_32x32x16_bf16 v[34:49], v[66:69], v[134:137], v[34:49]
	v_exp_f32_e32 v86, v86
	v_cvt_pk_bf16_f32 v70, v74, v75
	v_exp_f32_e32 v87, v87
	v_cvt_pk_bf16_f32 v71, v76, v77
	v_exp_f32_e32 v88, v88
	v_cvt_pk_bf16_f32 v72, v78, v79
	v_exp_f32_e32 v89, v89
	v_cvt_pk_bf16_f32 v73, v80, v81
	v_exp_f32_e32 v90, v90
	v_exp_f32_e32 v91, v91
	v_mfma_f32_32x32x16_bf16 v[18:33], v[70:73], v[146:149], v[18:33]
	v_exp_f32_e32 v92, v92
	v_pk_add_f32 v[154:155], v[82:83], v[84:85]
	v_exp_f32_e32 v93, v93
	v_pk_add_f32 v[156:157], v[86:87], v[88:89]
	v_exp_f32_e32 v94, v94
	v_pk_add_f32 v[162:163], v[154:155], v[156:157]
	s_waitcnt lgkmcnt(4)
	v_mfma_f32_32x32x16_bf16 v[34:49], v[70:73], v[130:133], v[34:49]
	v_exp_f32_e32 v95, v95
	v_cvt_pk_bf16_f32 v74, v82, v83
	v_exp_f32_e32 v96, v96
	v_cvt_pk_bf16_f32 v75, v84, v85
	v_exp_f32_e32 v97, v97
	v_cvt_pk_bf16_f32 v76, v86, v87
	v_cvt_pk_bf16_f32 v77, v88, v89
	v_pk_add_f32 v[154:155], v[90:91], v[92:93]
	v_pk_add_f32 v[156:157], v[94:95], v[96:97]
	v_mfma_f32_32x32x16_bf16 v[18:33], v[74:77], v[142:145], v[18:33]
	v_pk_add_f32 v[164:165], v[154:155], v[156:157]
	s_waitcnt lgkmcnt(2)
	v_mfma_f32_32x32x16_bf16 v[34:49], v[74:77], v[126:129], v[34:49]
	v_cvt_pk_bf16_f32 v78, v90, v91
	v_cvt_pk_bf16_f32 v79, v92, v93
	v_cvt_pk_bf16_f32 v80, v94, v95
	v_cvt_pk_bf16_f32 v81, v96, v97
	v_pk_add_f32 v[158:159], v[158:159], v[160:161]
	s_add_u32 s24, s24, 0x10000
	s_addc_u32 s25, s25, 0
	v_mfma_f32_32x32x16_bf16 v[18:33], v[78:81], v[138:141], v[18:33]
	v_pk_add_f32 v[162:163], v[162:163], v[164:165]
	s_add_u32 s22, s22, 0x1000
	s_addc_u32 s23, s23, 0
	s_waitcnt lgkmcnt(0)
	v_mfma_f32_32x32x16_bf16 v[34:49], v[78:81], v[122:125], v[34:49]
	v_pk_add_f32 v[158:159], v[158:159], v[162:163]
	v_add_f32_e32 v158, v158, v159
	v_add_u32_e32 v66, s56, v182
	v_add_f32_e32 v173, v173, v158
	v_add_u32_e32 v67, v66, v184
	v_add_u32_e32 v66, v66, v189
	s_cmp_eq_u32 s24, 0x200000
	s_waitcnt vmcnt(0) lgkmcnt(0)
	s_barrier
	ds_read_b128 v[82:85], v67
	s_cbranch_scc1 .LBB0_1484
	s_mov_b32 s49, s57
	s_mul_i32 s52, s49, 0x3000
	s_branch .Lmla2_reads2
